# residual epilogues: the last two quarters' stores issued after both quarters' FMAs, so the final load wait has no store acknowledgement ahead of it
# baseline (speedup 1.0000x reference)
.LBB0_163:
	s_andn2_b64 vcc, exec, s[72:73]
	s_cbranch_vccnz .LBB0_165
	v_lshlrev_b64 v[156:157], 13, v[194:195]
	v_lshl_add_u64 v[156:157], s[60:61], 0, v[156:157]
	v_lshlrev_b64 v[194:195], 2, v[182:183]
	v_lshl_add_u64 v[182:183], v[156:157], 0, v[194:195]
	v_mov_b32_e32 v160, v182
	v_mov_b32_e32 v161, v183
	global_load_dwordx4 v[200:203], v[182:183], off
	global_load_dwordx4 v[204:207], v[182:183], off offset:16
	global_load_dwordx4 v[208:211], v[182:183], off offset:512
	global_load_dwordx4 v[212:215], v[182:183], off offset:528
	s_mov_b64 s[44:45], 0x20000
	v_lshl_add_u64 v[182:183], v[182:183], 0, s[44:45]
	global_load_dwordx4 v[216:219], v[182:183], off
	global_load_dwordx4 v[220:223], v[182:183], off offset:16
	global_load_dwordx4 v[224:227], v[182:183], off offset:512
	global_load_dwordx4 v[228:231], v[182:183], off offset:528
	s_mov_b64 s[44:45], 0x20000
	v_lshl_add_u64 v[182:183], v[182:183], 0, s[44:45]
	s_waitcnt vmcnt(0)
	v_pk_fma_f32 v[132:133], v[132:133], v[148:149], v[202:203]
	v_pk_fma_f32 v[130:131], v[130:131], v[146:147], v[200:201]
	v_pk_fma_f32 v[128:129], v[128:129], v[144:145], v[206:207]
	v_pk_fma_f32 v[126:127], v[126:127], v[142:143], v[204:205]
	v_pk_fma_f32 v[100:101], v[100:101], v[140:141], v[210:211]
	v_pk_fma_f32 v[98:99], v[98:99], v[138:139], v[208:209]
	v_pk_fma_f32 v[96:97], v[96:97], v[136:137], v[214:215]
	v_pk_fma_f32 v[94:95], v[94:95], v[134:135], v[212:213]
	global_store_dwordx4 v[160:161], v[130:133], off
	global_store_dwordx4 v[160:161], v[126:129], off offset:16
	global_store_dwordx4 v[160:161], v[98:101], off offset:512
	global_store_dwordx4 v[160:161], v[94:97], off offset:528
	s_mov_b64 s[44:45], 0x20000
	v_lshl_add_u64 v[160:161], v[160:161], 0, s[44:45]
	v_pk_fma_f32 v[124:125], v[124:125], v[148:149], v[218:219]
	v_pk_fma_f32 v[122:123], v[122:123], v[146:147], v[216:217]
	v_pk_fma_f32 v[120:121], v[120:121], v[144:145], v[222:223]
	v_pk_fma_f32 v[118:119], v[118:119], v[142:143], v[220:221]
	v_pk_fma_f32 v[92:93], v[92:93], v[140:141], v[226:227]
	v_pk_fma_f32 v[90:91], v[90:91], v[138:139], v[224:225]
	v_pk_fma_f32 v[88:89], v[88:89], v[136:137], v[230:231]
	v_pk_fma_f32 v[86:87], v[86:87], v[134:135], v[228:229]
	global_store_dwordx4 v[160:161], v[122:125], off
	global_store_dwordx4 v[160:161], v[118:121], off offset:16
	global_store_dwordx4 v[160:161], v[90:93], off offset:512
	global_store_dwordx4 v[160:161], v[86:89], off offset:528
	s_mov_b64 s[44:45], 0x20000
	v_lshl_add_u64 v[160:161], v[160:161], 0, s[44:45]
	global_load_dwordx4 v[200:203], v[182:183], off
	global_load_dwordx4 v[204:207], v[182:183], off offset:16
	global_load_dwordx4 v[208:211], v[182:183], off offset:512
	global_load_dwordx4 v[212:215], v[182:183], off offset:528
	s_mov_b64 s[44:45], 0x20000
	v_lshl_add_u64 v[182:183], v[182:183], 0, s[44:45]
	global_load_dwordx4 v[216:219], v[182:183], off
	global_load_dwordx4 v[220:223], v[182:183], off offset:16
	global_load_dwordx4 v[224:227], v[182:183], off offset:512
	global_load_dwordx4 v[228:231], v[182:183], off offset:528
	s_mov_b64 s[44:45], 0xa0000
	v_lshl_add_u64 v[182:183], v[182:183], 0, s[44:45]
	global_load_dwordx4 v[130:133], v[182:183], off
	global_load_dwordx4 v[126:129], v[182:183], off offset:16
	global_load_dwordx4 v[98:101], v[182:183], off offset:512
	global_load_dwordx4 v[94:97], v[182:183], off offset:528
	s_mov_b64 s[44:45], 0x20000
	v_lshl_add_u64 v[182:183], v[182:183], 0, s[44:45]
	global_load_dwordx4 v[122:125], v[182:183], off
	global_load_dwordx4 v[118:121], v[182:183], off offset:16
	global_load_dwordx4 v[90:93], v[182:183], off offset:512
	global_load_dwordx4 v[86:89], v[182:183], off offset:528
	s_mov_b64 s[44:45], 0x20000
	v_lshl_add_u64 v[182:183], v[182:183], 0, s[44:45]
	s_waitcnt vmcnt(8)
	v_pk_fma_f32 v[116:117], v[116:117], v[148:149], v[202:203]
	v_pk_fma_f32 v[114:115], v[114:115], v[146:147], v[200:201]
	v_pk_fma_f32 v[112:113], v[112:113], v[144:145], v[206:207]
	v_pk_fma_f32 v[110:111], v[110:111], v[142:143], v[204:205]
	v_pk_fma_f32 v[84:85], v[84:85], v[140:141], v[210:211]
	v_pk_fma_f32 v[82:83], v[82:83], v[138:139], v[208:209]
	v_pk_fma_f32 v[80:81], v[80:81], v[136:137], v[214:215]
	v_pk_fma_f32 v[78:79], v[78:79], v[134:135], v[212:213]
	global_store_dwordx4 v[160:161], v[114:117], off
	global_store_dwordx4 v[160:161], v[110:113], off offset:16
	global_store_dwordx4 v[160:161], v[82:85], off offset:512
	global_store_dwordx4 v[160:161], v[78:81], off offset:528
	s_mov_b64 s[44:45], 0x20000
	v_lshl_add_u64 v[160:161], v[160:161], 0, s[44:45]
	v_pk_fma_f32 v[108:109], v[108:109], v[148:149], v[218:219]
	v_pk_fma_f32 v[106:107], v[106:107], v[146:147], v[216:217]
	v_pk_fma_f32 v[104:105], v[104:105], v[144:145], v[222:223]
	v_pk_fma_f32 v[102:103], v[102:103], v[142:143], v[220:221]
	v_pk_fma_f32 v[76:77], v[76:77], v[140:141], v[226:227]
	v_pk_fma_f32 v[74:75], v[74:75], v[138:139], v[224:225]
	v_pk_fma_f32 v[72:73], v[72:73], v[136:137], v[230:231]
	v_pk_fma_f32 v[70:71], v[70:71], v[134:135], v[228:229]
	global_store_dwordx4 v[160:161], v[106:109], off
	global_store_dwordx4 v[160:161], v[102:105], off offset:16
	global_store_dwordx4 v[160:161], v[74:77], off offset:512
	global_store_dwordx4 v[160:161], v[70:73], off offset:528
	s_mov_b64 s[44:45], 0xa0000
	v_lshl_add_u64 v[160:161], v[160:161], 0, s[44:45]
	global_load_dwordx4 v[200:203], v[182:183], off
	global_load_dwordx4 v[204:207], v[182:183], off offset:16
	global_load_dwordx4 v[208:211], v[182:183], off offset:512
	global_load_dwordx4 v[212:215], v[182:183], off offset:528
	s_mov_b64 s[44:45], 0x20000
	v_lshl_add_u64 v[182:183], v[182:183], 0, s[44:45]
	global_load_dwordx4 v[216:219], v[182:183], off
	global_load_dwordx4 v[220:223], v[182:183], off offset:16
	global_load_dwordx4 v[224:227], v[182:183], off offset:512
	global_load_dwordx4 v[228:231], v[182:183], off offset:528
	s_waitcnt vmcnt(8)
	v_pk_fma_f32 v[68:69], v[68:69], v[148:149], v[132:133]
	v_pk_fma_f32 v[66:67], v[66:67], v[146:147], v[130:131]
	v_pk_fma_f32 v[64:65], v[64:65], v[144:145], v[128:129]
	v_pk_fma_f32 v[62:63], v[62:63], v[142:143], v[126:127]
	v_pk_fma_f32 v[36:37], v[36:37], v[140:141], v[100:101]
	v_pk_fma_f32 v[34:35], v[34:35], v[138:139], v[98:99]
	v_pk_fma_f32 v[32:33], v[32:33], v[136:137], v[96:97]
	v_pk_fma_f32 v[30:31], v[30:31], v[134:135], v[94:95]
	v_pk_fma_f32 v[60:61], v[60:61], v[148:149], v[124:125]
	v_pk_fma_f32 v[58:59], v[58:59], v[146:147], v[122:123]
	v_pk_fma_f32 v[56:57], v[56:57], v[144:145], v[120:121]
	v_pk_fma_f32 v[54:55], v[54:55], v[142:143], v[118:119]
	v_pk_fma_f32 v[28:29], v[28:29], v[140:141], v[92:93]
	v_pk_fma_f32 v[26:27], v[26:27], v[138:139], v[90:91]
	v_pk_fma_f32 v[24:25], v[24:25], v[136:137], v[88:89]
	v_pk_fma_f32 v[22:23], v[22:23], v[134:135], v[86:87]
	s_waitcnt vmcnt(0)
	v_pk_fma_f32 v[52:53], v[52:53], v[148:149], v[202:203]
	v_pk_fma_f32 v[50:51], v[50:51], v[146:147], v[200:201]
	v_pk_fma_f32 v[48:49], v[48:49], v[144:145], v[206:207]
	v_pk_fma_f32 v[46:47], v[46:47], v[142:143], v[204:205]
	v_pk_fma_f32 v[20:21], v[20:21], v[140:141], v[210:211]
	v_pk_fma_f32 v[18:19], v[18:19], v[138:139], v[208:209]
	v_pk_fma_f32 v[12:13], v[12:13], v[136:137], v[214:215]
	v_pk_fma_f32 v[10:11], v[10:11], v[134:135], v[212:213]
	v_pk_fma_f32 v[44:45], v[44:45], v[148:149], v[218:219]
	v_pk_fma_f32 v[42:43], v[42:43], v[146:147], v[216:217]
	v_pk_fma_f32 v[40:41], v[40:41], v[144:145], v[222:223]
	v_pk_fma_f32 v[38:39], v[38:39], v[142:143], v[220:221]
	v_pk_fma_f32 v[8:9], v[8:9], v[140:141], v[226:227]
	v_pk_fma_f32 v[6:7], v[6:7], v[138:139], v[224:225]
	v_pk_fma_f32 v[2:3], v[2:3], v[136:137], v[230:231]
	v_pk_fma_f32 v[0:1], v[0:1], v[134:135], v[228:229]
	global_store_dwordx4 v[160:161], v[66:69], off
	global_store_dwordx4 v[160:161], v[62:65], off offset:16
	global_store_dwordx4 v[160:161], v[34:37], off offset:512
	global_store_dwordx4 v[160:161], v[30:33], off offset:528
	s_mov_b64 s[44:45], 0x20000
	v_lshl_add_u64 v[160:161], v[160:161], 0, s[44:45]
	global_store_dwordx4 v[160:161], v[58:61], off
	global_store_dwordx4 v[160:161], v[54:57], off offset:16
	global_store_dwordx4 v[160:161], v[26:29], off offset:512
	global_store_dwordx4 v[160:161], v[22:25], off offset:528
	s_mov_b64 s[44:45], 0x20000
	v_lshl_add_u64 v[160:161], v[160:161], 0, s[44:45]
	global_store_dwordx4 v[160:161], v[50:53], off
	global_store_dwordx4 v[160:161], v[46:49], off offset:16
	global_store_dwordx4 v[160:161], v[18:21], off offset:512
	global_store_dwordx4 v[160:161], v[10:13], off offset:528
	s_mov_b64 s[44:45], 0x20000
	v_lshl_add_u64 v[160:161], v[160:161], 0, s[44:45]
	global_store_dwordx4 v[160:161], v[42:45], off
	global_store_dwordx4 v[160:161], v[38:41], off offset:16
	global_store_dwordx4 v[160:161], v[6:9], off offset:512
	global_store_dwordx4 v[160:161], v[0:3], off offset:528

.LBB0_192:
	s_lshl_b32 s44, s0, 8
	v_add_u32_e32 v186, s44, v5
	s_addk_i32 s44, 0xf000
	s_ashr_i32 s44, s44, 10
	s_add_i32 s44, s44, 1
	s_cmp_lt_i32 s0, 16
	v_lshl_or_b32 v184, s82, 8, v153
	s_cselect_b32 s0, 0, s44
	v_ashrrev_i32_e32 v187, 31, v186
	v_ashrrev_i32_e32 v185, 31, v184
	s_mul_hi_i32 s45, s0, 0xc000
	s_mul_i32 s0, s0, 0xc000
	v_lshlrev_b64 v[156:157], 11, v[186:187]
	s_cselect_b32 s73, s11, s13
	s_cselect_b32 s72, s10, s12
	s_add_u32 s44, s42, s0
	v_lshl_add_u64 v[156:157], v[156:157], 0, v[184:185]
	s_addc_u32 s45, s64, s45
	v_lshlrev_b64 v[182:183], 2, v[156:157]
	v_lshl_add_u64 v[134:135], v[184:185], 2, s[44:45]
	v_lshl_add_u64 v[160:161], s[72:73], 0, v[182:183]
	global_load_dwordx4 v[138:141], v[134:135], off offset:16
	global_load_dwordx4 v[146:149], v[134:135], off
	global_load_dwordx4 v[130:133], v[134:135], off offset:528
	s_nop 0
	global_load_dwordx4 v[134:137], v[134:135], off offset:512
	s_and_b64 vcc, exec, s[6:7]
	v_lshl_add_u64 v[156:157], s[60:61], 0, v[182:183]
	global_load_dwordx4 v[190:193], v[160:161], off
	global_load_dwordx4 v[194:197], v[160:161], off offset:16
	global_load_dwordx4 v[198:201], v[160:161], off offset:512
	global_load_dwordx4 v[202:205], v[160:161], off offset:528
	s_mov_b64 s[44:45], 0x20000
	v_lshl_add_u64 v[160:161], v[160:161], 0, s[44:45]
	global_load_dwordx4 v[206:209], v[160:161], off
	global_load_dwordx4 v[210:213], v[160:161], off offset:16
	global_load_dwordx4 v[214:217], v[160:161], off offset:512
	global_load_dwordx4 v[218:221], v[160:161], off offset:528
	s_mov_b64 s[44:45], 0x20000
	v_lshl_add_u64 v[160:161], v[160:161], 0, s[44:45]
	s_waitcnt vmcnt(0)
	v_pk_fma_f32 v[144:145], v[144:145], v[148:149], v[192:193]
	v_pk_fma_f32 v[142:143], v[142:143], v[146:147], v[190:191]
	v_pk_fma_f32 v[128:129], v[128:129], v[140:141], v[196:197]
	v_pk_fma_f32 v[126:127], v[126:127], v[138:139], v[194:195]
	v_pk_fma_f32 v[124:125], v[124:125], v[136:137], v[200:201]
	v_pk_fma_f32 v[122:123], v[122:123], v[134:135], v[198:199]
	v_pk_fma_f32 v[120:121], v[120:121], v[132:133], v[204:205]
	v_pk_fma_f32 v[118:119], v[118:119], v[130:131], v[202:203]
	global_store_dwordx4 v[156:157], v[142:145], off
	global_store_dwordx4 v[156:157], v[126:129], off offset:16
	global_store_dwordx4 v[156:157], v[122:125], off offset:512
	global_store_dwordx4 v[156:157], v[118:121], off offset:528
	s_mov_b64 s[44:45], 0x20000
	v_lshl_add_u64 v[156:157], v[156:157], 0, s[44:45]
	v_pk_fma_f32 v[116:117], v[116:117], v[148:149], v[208:209]
	v_pk_fma_f32 v[114:115], v[114:115], v[146:147], v[206:207]
	v_pk_fma_f32 v[112:113], v[112:113], v[140:141], v[212:213]
	v_pk_fma_f32 v[110:111], v[110:111], v[138:139], v[210:211]
	v_pk_fma_f32 v[108:109], v[108:109], v[136:137], v[216:217]
	v_pk_fma_f32 v[106:107], v[106:107], v[134:135], v[214:215]
	v_pk_fma_f32 v[104:105], v[104:105], v[132:133], v[220:221]
	v_pk_fma_f32 v[102:103], v[102:103], v[130:131], v[218:219]
	global_store_dwordx4 v[156:157], v[114:117], off
	global_store_dwordx4 v[156:157], v[110:113], off offset:16
	global_store_dwordx4 v[156:157], v[106:109], off offset:512
	global_store_dwordx4 v[156:157], v[102:105], off offset:528
	s_mov_b64 s[44:45], 0x20000
	v_lshl_add_u64 v[156:157], v[156:157], 0, s[44:45]
	global_load_dwordx4 v[190:193], v[160:161], off
	global_load_dwordx4 v[194:197], v[160:161], off offset:16
	global_load_dwordx4 v[198:201], v[160:161], off offset:512
	global_load_dwordx4 v[202:205], v[160:161], off offset:528
	s_mov_b64 s[44:45], 0x20000
	v_lshl_add_u64 v[160:161], v[160:161], 0, s[44:45]
	global_load_dwordx4 v[206:209], v[160:161], off
	global_load_dwordx4 v[210:213], v[160:161], off offset:16
	global_load_dwordx4 v[214:217], v[160:161], off offset:512
	global_load_dwordx4 v[218:221], v[160:161], off offset:528
	s_mov_b64 s[44:45], 0xa0000
	v_lshl_add_u64 v[160:161], v[160:161], 0, s[44:45]
	global_load_dwordx4 v[142:145], v[160:161], off
	global_load_dwordx4 v[126:129], v[160:161], off offset:16
	global_load_dwordx4 v[122:125], v[160:161], off offset:512
	global_load_dwordx4 v[118:121], v[160:161], off offset:528
	s_mov_b64 s[44:45], 0x20000
	v_lshl_add_u64 v[160:161], v[160:161], 0, s[44:45]
	global_load_dwordx4 v[114:117], v[160:161], off
	global_load_dwordx4 v[110:113], v[160:161], off offset:16
	global_load_dwordx4 v[106:109], v[160:161], off offset:512
	global_load_dwordx4 v[102:105], v[160:161], off offset:528
	s_mov_b64 s[44:45], 0x20000
	v_lshl_add_u64 v[160:161], v[160:161], 0, s[44:45]
	s_waitcnt vmcnt(8)
	v_pk_fma_f32 v[100:101], v[100:101], v[148:149], v[192:193]
	v_pk_fma_f32 v[98:99], v[98:99], v[146:147], v[190:191]
	v_pk_fma_f32 v[96:97], v[96:97], v[140:141], v[196:197]
	v_pk_fma_f32 v[94:95], v[94:95], v[138:139], v[194:195]
	v_pk_fma_f32 v[92:93], v[92:93], v[136:137], v[200:201]
	v_pk_fma_f32 v[90:91], v[90:91], v[134:135], v[198:199]
	v_pk_fma_f32 v[88:89], v[88:89], v[132:133], v[204:205]
	v_pk_fma_f32 v[86:87], v[86:87], v[130:131], v[202:203]
	global_store_dwordx4 v[156:157], v[98:101], off
	global_store_dwordx4 v[156:157], v[94:97], off offset:16
	global_store_dwordx4 v[156:157], v[90:93], off offset:512
	global_store_dwordx4 v[156:157], v[86:89], off offset:528
	s_mov_b64 s[44:45], 0x20000
	v_lshl_add_u64 v[156:157], v[156:157], 0, s[44:45]
	v_pk_fma_f32 v[84:85], v[84:85], v[148:149], v[208:209]
	v_pk_fma_f32 v[82:83], v[82:83], v[146:147], v[206:207]
	v_pk_fma_f32 v[80:81], v[80:81], v[140:141], v[212:213]
	v_pk_fma_f32 v[78:79], v[78:79], v[138:139], v[210:211]
	v_pk_fma_f32 v[76:77], v[76:77], v[136:137], v[216:217]
	v_pk_fma_f32 v[74:75], v[74:75], v[134:135], v[214:215]
	v_pk_fma_f32 v[72:73], v[72:73], v[132:133], v[220:221]
	v_pk_fma_f32 v[70:71], v[70:71], v[130:131], v[218:219]
	global_store_dwordx4 v[156:157], v[82:85], off
	global_store_dwordx4 v[156:157], v[78:81], off offset:16
	global_store_dwordx4 v[156:157], v[74:77], off offset:512
	global_store_dwordx4 v[156:157], v[70:73], off offset:528
	s_mov_b64 s[44:45], 0xa0000
	v_lshl_add_u64 v[156:157], v[156:157], 0, s[44:45]
	global_load_dwordx4 v[190:193], v[160:161], off
	global_load_dwordx4 v[194:197], v[160:161], off offset:16
	global_load_dwordx4 v[198:201], v[160:161], off offset:512
	global_load_dwordx4 v[202:205], v[160:161], off offset:528
	s_mov_b64 s[44:45], 0x20000
	v_lshl_add_u64 v[160:161], v[160:161], 0, s[44:45]
	global_load_dwordx4 v[206:209], v[160:161], off
	global_load_dwordx4 v[210:213], v[160:161], off offset:16
	global_load_dwordx4 v[214:217], v[160:161], off offset:512
	global_load_dwordx4 v[218:221], v[160:161], off offset:528
	s_waitcnt vmcnt(8)
	v_pk_fma_f32 v[68:69], v[68:69], v[148:149], v[144:145]
	v_pk_fma_f32 v[66:67], v[66:67], v[146:147], v[142:143]
	v_pk_fma_f32 v[64:65], v[64:65], v[140:141], v[128:129]
	v_pk_fma_f32 v[62:63], v[62:63], v[138:139], v[126:127]
	v_pk_fma_f32 v[60:61], v[60:61], v[136:137], v[124:125]
	v_pk_fma_f32 v[58:59], v[58:59], v[134:135], v[122:123]
	v_pk_fma_f32 v[56:57], v[56:57], v[132:133], v[120:121]
	v_pk_fma_f32 v[54:55], v[54:55], v[130:131], v[118:119]
	v_pk_fma_f32 v[52:53], v[52:53], v[148:149], v[116:117]
	v_pk_fma_f32 v[50:51], v[50:51], v[146:147], v[114:115]
	v_pk_fma_f32 v[48:49], v[48:49], v[140:141], v[112:113]
	v_pk_fma_f32 v[46:47], v[46:47], v[138:139], v[110:111]
	v_pk_fma_f32 v[44:45], v[44:45], v[136:137], v[108:109]
	v_pk_fma_f32 v[42:43], v[42:43], v[134:135], v[106:107]
	v_pk_fma_f32 v[40:41], v[40:41], v[132:133], v[104:105]
	v_pk_fma_f32 v[38:39], v[38:39], v[130:131], v[102:103]
	s_waitcnt vmcnt(0)
	v_pk_fma_f32 v[36:37], v[36:37], v[148:149], v[192:193]
	v_pk_fma_f32 v[34:35], v[34:35], v[146:147], v[190:191]
	v_pk_fma_f32 v[32:33], v[32:33], v[140:141], v[196:197]
	v_pk_fma_f32 v[30:31], v[30:31], v[138:139], v[194:195]
	v_pk_fma_f32 v[28:29], v[28:29], v[136:137], v[200:201]
	v_pk_fma_f32 v[26:27], v[26:27], v[134:135], v[198:199]
	v_pk_fma_f32 v[24:25], v[24:25], v[132:133], v[204:205]
	v_pk_fma_f32 v[22:23], v[22:23], v[130:131], v[202:203]
	v_pk_fma_f32 v[20:21], v[20:21], v[148:149], v[208:209]
	v_pk_fma_f32 v[18:19], v[18:19], v[146:147], v[206:207]
	v_pk_fma_f32 v[12:13], v[12:13], v[140:141], v[212:213]
	v_pk_fma_f32 v[10:11], v[10:11], v[138:139], v[210:211]
	v_pk_fma_f32 v[8:9], v[8:9], v[136:137], v[216:217]
	v_pk_fma_f32 v[6:7], v[6:7], v[134:135], v[214:215]
	v_pk_fma_f32 v[2:3], v[2:3], v[132:133], v[220:221]
	v_pk_fma_f32 v[0:1], v[0:1], v[130:131], v[218:219]
	global_store_dwordx4 v[156:157], v[66:69], off
	global_store_dwordx4 v[156:157], v[62:65], off offset:16
	global_store_dwordx4 v[156:157], v[58:61], off offset:512
	global_store_dwordx4 v[156:157], v[54:57], off offset:528
	s_mov_b64 s[44:45], 0x20000
	v_lshl_add_u64 v[156:157], v[156:157], 0, s[44:45]
	global_store_dwordx4 v[156:157], v[50:53], off
	global_store_dwordx4 v[156:157], v[46:49], off offset:16
	global_store_dwordx4 v[156:157], v[42:45], off offset:512
	global_store_dwordx4 v[156:157], v[38:41], off offset:528
	s_mov_b64 s[44:45], 0x20000
	v_lshl_add_u64 v[156:157], v[156:157], 0, s[44:45]
	global_store_dwordx4 v[156:157], v[34:37], off
	global_store_dwordx4 v[156:157], v[30:33], off offset:16
	global_store_dwordx4 v[156:157], v[26:29], off offset:512
	global_store_dwordx4 v[156:157], v[22:25], off offset:528
	s_mov_b64 s[44:45], 0x20000
	v_lshl_add_u64 v[156:157], v[156:157], 0, s[44:45]
	global_store_dwordx4 v[156:157], v[18:21], off
	global_store_dwordx4 v[156:157], v[10:13], off offset:16
	global_store_dwordx4 v[156:157], v[6:9], off offset:512
	global_store_dwordx4 v[156:157], v[0:3], off offset:528
	s_mov_b64 s[72:73], -1
	s_cbranch_vccnz .LBB0_181
	s_andn2_b64 vcc, exec, s[66:67]
	s_cbranch_vccnz .LBB0_180
	s_barrier
	s_branch .LBB0_180
